# P0 tables: rope pos loads and lbT loads issued at section start (latency hidden behind zero-fill loops)
# speedup vs baseline: 1.0005x; 1.0005x over previous
.LBB0_44:
	v_writelane_b32 v246, s16, 20
	s_nop 1
	v_writelane_b32 v246, s17, 21
	v_writelane_b32 v246, s18, 22
	v_writelane_b32 v246, s19, 23
	v_writelane_b32 v246, s20, 24
	v_writelane_b32 v246, s21, 25
	v_writelane_b32 v246, s22, 26
	v_writelane_b32 v246, s23, 27
	v_writelane_b32 v246, s24, 28
	v_writelane_b32 v246, s25, 29
	v_writelane_b32 v246, s26, 30
	v_writelane_b32 v246, s27, 31
	v_writelane_b32 v246, s28, 32
	v_writelane_b32 v246, s29, 33
	v_writelane_b32 v246, s30, 34
	v_writelane_b32 v246, s31, 35
	s_or_b64 exec, exec, s[0:1]
	s_lshl_b32 s84, s64, 9
	v_add_u32_e32 v6, s84, v69
	s_mov_b32 s0, 0xc000
	s_lshl_b32 s52, s65, 9
	v_cmp_gt_i32_e32 vcc, s0, v6
	v_ashrrev_i32_e32 v7, 31, v6
	v_ashrrev_i32_e32 v134, 5, v6
	v_add_u32_e32 v138, s52, v6
	v_ashrrev_i32_e32 v135, 5, v138
	v_add_u32_e32 v138, s52, v138
	v_ashrrev_i32_e32 v136, 5, v138
	v_add_u32_e32 v138, s52, v138
	v_ashrrev_i32_e32 v137, 5, v138
	v_lshlrev_b32_e32 v134, 2, v134
	v_lshlrev_b32_e32 v135, 2, v135
	v_lshlrev_b32_e32 v136, 2, v136
	v_lshlrev_b32_e32 v137, 2, v137
	global_load_dword v134, v134, s[18:19]
	global_load_dword v135, v135, s[18:19]
	global_load_dword v136, v136, s[18:19]
	global_load_dword v137, v137, s[18:19]
	s_movk_i32 s98, 0x400
	v_cmp_gt_i32_e64 s[98:99], s98, v6
	s_and_saveexec_b64 s[98:99], s[98:99]
	v_lshlrev_b32_e32 v139, 2, v6
	v_add_u32_e32 v140, 0x1000, v139
	global_load_dword v140, v140, s[24:25]
	global_load_dword v139, v139, s[24:25]
	s_or_b64 exec, exec, s[98:99]
	s_and_saveexec_b64 s[0:1], vcc
	s_cbranch_execz .LBB0_47
	v_lshl_add_u64 v[2:3], v[6:7], 4, s[90:91]
	s_mov_b64 s[2:3], 0x1440000
	v_lshl_add_u64 v[8:9], v[2:3], 0, s[2:3]
	s_ashr_i32 s53, s52, 31
	v_mov_b32_e32 v2, 0
	s_lshl_b64 s[2:3], s[52:53], 4
	s_mov_b64 s[4:5], 0
	v_mov_b32_e32 v3, v2
	v_mov_b32_e32 v4, v2
	v_mov_b32_e32 v5, v2
	s_mov_b32 s8, 0xbfff
	v_mov_b32_e32 v1, v6

.LBB0_57:
	v_lshl_add_u64 v[4:5], s[16:17], 0, v[2:3]
	v_add_co_u32_e32 v8, vcc, 0x1000, v4
	v_add_u32_e32 v1, s52, v1
	s_nop 0
	v_addc_co_u32_e32 v9, vcc, 0, v5, vcc
	s_nop 0
	s_nop 0
	s_nop 0
	v_cmp_lt_i32_e32 vcc, s8, v1
	s_or_b64 s[4:5], vcc, s[4:5]
	v_lshl_add_u64 v[4:5], s[54:55], 0, v[2:3]
	v_lshl_add_u64 v[2:3], v[2:3], 0, s[2:3]
	s_waitcnt vmcnt(0)
	v_mov_b32_e32 v8, v140
	v_mov_b32_e32 v9, v139
	v_sub_f32_e32 v8, v8, v9
	v_mul_f32_e32 v8, 0x3fb8aa3b, v8
	v_exp_f32_e32 v8, v8
	s_nop 0
	v_add_f32_e32 v8, 1.0, v8
	v_div_scale_f32 v9, s[10:11], v8, v8, 1.0
	v_rcp_f32_e32 v10, v9
	v_div_scale_f32 v11, vcc, 1.0, v8, 1.0
	v_fma_f32 v12, -v9, v10, 1.0
	v_fmac_f32_e32 v10, v12, v10
	v_mul_f32_e32 v12, v11, v10
	v_fma_f32 v13, -v9, v12, v11
	v_fmac_f32_e32 v12, v13, v10
	v_fma_f32 v9, -v9, v12, v11
	v_div_fmas_f32 v9, v9, v10, v12
	v_div_fixup_f32 v8, v9, v8, 1.0
	global_store_dword v[4:5], v8, off
	s_andn2_b64 exec, exec, s[4:5]
	s_cbranch_execnz .LBB0_57
.LBB0_58:
	s_or_b64 exec, exec, s[0:1]
	s_mov_b32 s0, 0x80000
	v_cmp_gt_i32_e32 vcc, s0, v6
	s_and_saveexec_b64 s[0:1], vcc
	s_cbranch_execz .LBB0_69
	v_and_b32_e32 v1, 31, v69
	s_mov_b32 s2, 0xbbb55516
	v_cvt_f64_u32_e32 v[2:3], v1
	s_mov_b32 s3, 0xbfd26bb1
	v_mul_f64 v[8:9], v[2:3], s[2:3]
	s_mov_b32 s2, 0x652b82fe
	s_mov_b32 s3, 0x3ff71547
	v_mul_f64 v[2:3], v[8:9], s[2:3]
	s_mov_b32 s2, 0xfefa39ef
	v_rndne_f64_e32 v[10:11], v[2:3]
	s_mov_b32 s3, 0xbfe62e42
	v_fma_f64 v[12:13], s[2:3], v[10:11], v[8:9]
	s_mov_b32 s2, 0x3b39803f
	s_mov_b32 s3, 0xbc7abc9e
	v_fmac_f64_e32 v[12:13], s[2:3], v[10:11]
	s_mov_b32 s2, 0x6a5dcb37
	v_mov_b32_e32 v2, 0xfca7ab0c
	v_mov_b32_e32 v3, 0x3e928af3
	s_mov_b32 s3, 0x3e5ade15
	v_fmac_f64_e32 v[2:3], s[2:3], v[12:13]
	v_mov_b32_e32 v4, 0x623fde64
	v_mov_b32_e32 v5, 0x3ec71dee
	v_fmac_f64_e32 v[4:5], v[12:13], v[2:3]
	v_mov_b32_e32 v2, 0x7c89e6b0
	v_mov_b32_e32 v3, 0x3efa0199
	v_fmac_f64_e32 v[2:3], v[12:13], v[4:5]
	v_mov_b32_e32 v4, 0x14761f6e
	v_mov_b32_e32 v5, 0x3f2a01a0
	v_fmac_f64_e32 v[4:5], v[12:13], v[2:3]
	v_mov_b32_e32 v14, 0x1852b7b0
	v_mov_b32_e32 v15, 0x3f56c16c
	v_mov_b32_e32 v2, 0x11122322
	v_mov_b32_e32 v3, 0x3f811111
	v_fmac_f64_e32 v[14:15], v[12:13], v[4:5]
	v_mov_b64_e32 v[16:17], v[2:3]
	v_mov_b32_e32 v4, 0x555502a1
	v_mov_b32_e32 v5, 0x3fa55555
	v_fmac_f64_e32 v[16:17], v[12:13], v[14:15]
	v_mov_b64_e32 v[14:15], v[4:5]
	v_fmac_f64_e32 v[14:15], v[12:13], v[16:17]
	v_mov_b32_e32 v16, 0x55555511
	v_mov_b32_e32 v17, 0x3fc55555
	v_fmac_f64_e32 v[16:17], v[12:13], v[14:15]
	v_mov_b32_e32 v14, 11
	v_mov_b32_e32 v15, 0x3fe00000
	s_mov_b32 s2, 0
	v_fmac_f64_e32 v[14:15], v[12:13], v[16:17]
	s_mov_b32 s3, 0x40900000
	v_fma_f64 v[14:15], v[12:13], v[14:15], 1.0
	v_cmp_nlt_f64_e32 vcc, s[2:3], v[8:9]
	s_mov_b32 s2, 0
	v_fma_f64 v[12:13], v[12:13], v[14:15], 1.0
	v_cvt_i32_f64_e32 v1, v[10:11]
	s_mov_b32 s3, 0xc090cc00
	v_ldexp_f64 v[10:11], v[12:13], v1
	v_mov_b32_e32 v1, 0x7ff00000
	v_cmp_ngt_f64_e64 s[2:3], s[2:3], v[8:9]
	v_cndmask_b32_e32 v1, v1, v11, vcc
	s_and_b64 vcc, s[2:3], vcc
	v_cndmask_b32_e64 v9, 0, v1, s[2:3]
	v_cndmask_b32_e32 v8, 0, v10, vcc
	v_cvt_f32_f64_e32 v1, v[8:9]
	v_lshl_add_u64 v[8:9], v[6:7], 2, s[90:91]
	s_mov_b64 s[2:3], 0x1e400000
	s_ashr_i32 s53, s52, 31
	s_mov_b32 s20, 0x6dc9c883
	s_mov_b32 s34, 0x54442d18
	s_mov_b32 s56, 0x67f544e4
	v_mov_b32_e32 v12, 0x1a01a01a
	v_mov_b32_e32 v14, 0x55555555
	s_mov_b32 s58, 0xeff8d898
	v_lshl_add_u64 v[8:9], v[8:9], 0, s[2:3]
	s_lshl_b64 s[2:3], s[52:53], 2
	s_mov_b64 s[4:5], 0
	s_mov_b32 s21, 0x3fe45f30
	s_mov_b32 s35, 0xbff921fb
	v_mov_b32_e32 v10, 0xa556c734
	v_mov_b32_e32 v11, 0x3ec71de3
	s_mov_b32 s57, 0xbe5ae645
	v_mov_b32_e32 v13, 0xbf2a01a0
	v_mov_b32_e32 v2, 0x11111111
	v_mov_b32_e32 v15, 0xbfc55555
	v_mov_b32_e32 v16, 0xb7789f5c
	v_mov_b32_e32 v17, 0xbe927e4f
	s_mov_b32 s59, 0x3e21eed8
	v_mov_b32_e32 v19, 0x3efa01a0
	v_mov_b32_e32 v18, v12
	v_mov_b32_e32 v20, 0x16c16c17
	v_mov_b32_e32 v21, 0xbf56c16c
	v_mov_b32_e32 v4, v14
	s_mov_b32 s12, 0x7ffff
	s_waitcnt vmcnt(0)
	s_branch .LBB0_62
